# GEMM main-loop heads aligned to 64 B (on top of G2 loop + lean past-K epilogue)
# baseline (speedup 1.0000x reference)
.LBB0_211:
	s_ashr_i32 s49, s48, 31
	s_lshl_b64 s[52:53], s[48:49], 20
	s_add_u32 s52, s9, s52
	s_addc_u32 s53, s10, s53
	s_and_b64 s[54:55], s[42:43], exec
	s_cselect_b32 s13, s53, s45
	s_cselect_b32 s49, s52, s44
	s_ashr_i32 s39, s38, 31
	s_lshl_b64 s[54:55], s[38:39], 20
	s_add_u32 s54, s11, s54
	s_addc_u32 s55, s33, s55
	s_and_b64 s[56:57], s[42:43], exec
	s_cselect_b32 s39, s55, s47
	s_cselect_b32 s58, s54, s46
	s_add_u32 s44, s44, 0x80080
	s_addc_u32 s45, s45, 0
	s_add_u32 s59, s46, 0x100
	v_mov_b32_e32 v4, 0
	s_addc_u32 s62, s47, 0
	s_mov_b32 s63, -2
	v_mov_b32_e32 v5, v4
	v_mov_b32_e32 v6, v4
	v_mov_b32_e32 v7, v4
	v_mov_b32_e32 v8, v4
	v_mov_b32_e32 v9, v4
	v_mov_b32_e32 v10, v4
	v_mov_b32_e32 v11, v4
	v_mov_b32_e32 v12, v4
	v_mov_b32_e32 v13, v4
	v_mov_b32_e32 v14, v4
	v_mov_b32_e32 v15, v4
	v_mov_b32_e32 v16, v4
	v_mov_b32_e32 v17, v4
	v_mov_b32_e32 v18, v4
	v_mov_b32_e32 v19, v4
	v_mov_b32_e32 v24, v4
	v_mov_b32_e32 v25, v4
	v_mov_b32_e32 v26, v4
	v_mov_b32_e32 v27, v4
	v_mov_b32_e32 v32, v4
	v_mov_b32_e32 v33, v4
	v_mov_b32_e32 v34, v4
	v_mov_b32_e32 v35, v4
	v_mov_b32_e32 v40, v4
	v_mov_b32_e32 v41, v4
	v_mov_b32_e32 v42, v4
	v_mov_b32_e32 v43, v4
	v_mov_b32_e32 v48, v4
	v_mov_b32_e32 v49, v4
	v_mov_b32_e32 v50, v4
	v_mov_b32_e32 v51, v4
	v_mov_b32_e32 v20, v4
	v_mov_b32_e32 v21, v4
	v_mov_b32_e32 v22, v4
	v_mov_b32_e32 v23, v4
	v_mov_b32_e32 v28, v4
	v_mov_b32_e32 v29, v4
	v_mov_b32_e32 v30, v4
	v_mov_b32_e32 v31, v4
	v_mov_b32_e32 v36, v4
	v_mov_b32_e32 v37, v4
	v_mov_b32_e32 v38, v4
	v_mov_b32_e32 v39, v4
	v_mov_b32_e32 v44, v4
	v_mov_b32_e32 v45, v4
	v_mov_b32_e32 v46, v4
	v_mov_b32_e32 v47, v4
	v_mov_b32_e32 v52, v4
	v_mov_b32_e32 v53, v4
	v_mov_b32_e32 v54, v4
	v_mov_b32_e32 v55, v4
	v_mov_b32_e32 v56, v4
	v_mov_b32_e32 v57, v4
	v_mov_b32_e32 v58, v4
	v_mov_b32_e32 v59, v4
	v_mov_b32_e32 v60, v4
	v_mov_b32_e32 v61, v4
	v_mov_b32_e32 v62, v4
	v_mov_b32_e32 v63, v4
	v_mov_b32_e32 v64, v4
	v_mov_b32_e32 v65, v4
	v_mov_b32_e32 v66, v4
	v_mov_b32_e32 v67, v4
	v_mov_b32_e32 v68, v4
	v_mov_b32_e32 v69, v4
	v_mov_b32_e32 v70, v4
	v_mov_b32_e32 v71, v4
	v_mov_b32_e32 v72, v4
	v_mov_b32_e32 v73, v4
	v_mov_b32_e32 v74, v4
	v_mov_b32_e32 v75, v4
	v_mov_b32_e32 v76, v4
	v_mov_b32_e32 v77, v4
	v_mov_b32_e32 v78, v4
	v_mov_b32_e32 v79, v4
	v_mov_b32_e32 v80, v4
	v_mov_b32_e32 v81, v4
	v_mov_b32_e32 v82, v4
	v_mov_b32_e32 v83, v4
	v_mov_b32_e32 v88, v4
	v_mov_b32_e32 v89, v4
	v_mov_b32_e32 v90, v4
	v_mov_b32_e32 v91, v4
	v_mov_b32_e32 v96, v4
	v_mov_b32_e32 v97, v4
	v_mov_b32_e32 v98, v4
	v_mov_b32_e32 v99, v4
	v_mov_b32_e32 v104, v4
	v_mov_b32_e32 v105, v4
	v_mov_b32_e32 v106, v4
	v_mov_b32_e32 v107, v4
	v_mov_b32_e32 v112, v4
	v_mov_b32_e32 v113, v4
	v_mov_b32_e32 v114, v4
	v_mov_b32_e32 v115, v4
	v_mov_b32_e32 v84, v4
	v_mov_b32_e32 v85, v4
	v_mov_b32_e32 v86, v4
	v_mov_b32_e32 v87, v4
	v_mov_b32_e32 v92, v4
	v_mov_b32_e32 v93, v4
	v_mov_b32_e32 v94, v4
	v_mov_b32_e32 v95, v4
	v_mov_b32_e32 v100, v4
	v_mov_b32_e32 v101, v4
	v_mov_b32_e32 v102, v4
	v_mov_b32_e32 v103, v4
	v_mov_b32_e32 v108, v4
	v_mov_b32_e32 v109, v4
	v_mov_b32_e32 v110, v4
	v_mov_b32_e32 v111, v4
	v_mov_b32_e32 v116, v4
	v_mov_b32_e32 v117, v4
	v_mov_b32_e32 v118, v4
	v_mov_b32_e32 v119, v4
	v_mov_b32_e32 v120, v4
	v_mov_b32_e32 v121, v4
	v_mov_b32_e32 v122, v4
	v_mov_b32_e32 v123, v4
	v_mov_b32_e32 v124, v4
	v_mov_b32_e32 v125, v4
	v_mov_b32_e32 v126, v4
	v_mov_b32_e32 v127, v4
	v_mov_b32_e32 v128, v4
	v_mov_b32_e32 v129, v4
	v_mov_b32_e32 v130, v4
	v_mov_b32_e32 v131, v4
	.p2align	6

.LBB0_315:
	s_ashr_i32 s23, s22, 31
	s_lshl_b64 s[26:27], s[22:23], 20
	s_add_u32 s26, s9, s26
	s_addc_u32 s27, s10, s27
	s_and_b64 s[28:29], s[24:25], exec
	s_cselect_b32 s23, s27, s31
	s_cselect_b32 s48, s26, s30
	s_ashr_i32 s21, s20, 31
	s_lshl_b64 s[28:29], s[20:21], 20
	s_add_u32 s28, s11, s28
	s_addc_u32 s29, s33, s29
	s_and_b64 s[36:37], s[24:25], exec
	s_cselect_b32 s21, s29, s35
	s_cselect_b32 s49, s28, s34
	s_add_u32 s30, s30, 0x80080
	s_addc_u32 s31, s31, 0
	s_add_u32 s52, s34, 0x100
	v_mov_b32_e32 v4, 0
	s_addc_u32 s53, s35, 0
	s_mov_b32 s54, -2
	v_mov_b32_e32 v5, v4
	v_mov_b32_e32 v6, v4
	v_mov_b32_e32 v7, v4
	v_mov_b32_e32 v8, v4
	v_mov_b32_e32 v9, v4
	v_mov_b32_e32 v10, v4
	v_mov_b32_e32 v11, v4
	v_mov_b32_e32 v12, v4
	v_mov_b32_e32 v13, v4
	v_mov_b32_e32 v14, v4
	v_mov_b32_e32 v15, v4
	v_mov_b32_e32 v16, v4
	v_mov_b32_e32 v17, v4
	v_mov_b32_e32 v18, v4
	v_mov_b32_e32 v19, v4
	v_mov_b32_e32 v28, v4
	v_mov_b32_e32 v29, v4
	v_mov_b32_e32 v30, v4
	v_mov_b32_e32 v31, v4
	v_mov_b32_e32 v32, v4
	v_mov_b32_e32 v33, v4
	v_mov_b32_e32 v34, v4
	v_mov_b32_e32 v35, v4
	v_mov_b32_e32 v44, v4
	v_mov_b32_e32 v45, v4
	v_mov_b32_e32 v46, v4
	v_mov_b32_e32 v47, v4
	v_mov_b32_e32 v48, v4
	v_mov_b32_e32 v49, v4
	v_mov_b32_e32 v50, v4
	v_mov_b32_e32 v51, v4
	v_mov_b32_e32 v20, v4
	v_mov_b32_e32 v21, v4
	v_mov_b32_e32 v22, v4
	v_mov_b32_e32 v23, v4
	v_mov_b32_e32 v24, v4
	v_mov_b32_e32 v25, v4
	v_mov_b32_e32 v26, v4
	v_mov_b32_e32 v27, v4
	v_mov_b32_e32 v36, v4
	v_mov_b32_e32 v37, v4
	v_mov_b32_e32 v38, v4
	v_mov_b32_e32 v39, v4
	v_mov_b32_e32 v40, v4
	v_mov_b32_e32 v41, v4
	v_mov_b32_e32 v42, v4
	v_mov_b32_e32 v43, v4
	v_mov_b32_e32 v52, v4
	v_mov_b32_e32 v53, v4
	v_mov_b32_e32 v54, v4
	v_mov_b32_e32 v55, v4
	v_mov_b32_e32 v56, v4
	v_mov_b32_e32 v57, v4
	v_mov_b32_e32 v58, v4
	v_mov_b32_e32 v59, v4
	v_mov_b32_e32 v60, v4
	v_mov_b32_e32 v61, v4
	v_mov_b32_e32 v62, v4
	v_mov_b32_e32 v63, v4
	v_mov_b32_e32 v64, v4
	v_mov_b32_e32 v65, v4
	v_mov_b32_e32 v66, v4
	v_mov_b32_e32 v67, v4
	v_mov_b32_e32 v68, v4
	v_mov_b32_e32 v69, v4
	v_mov_b32_e32 v70, v4
	v_mov_b32_e32 v71, v4
	v_mov_b32_e32 v72, v4
	v_mov_b32_e32 v73, v4
	v_mov_b32_e32 v74, v4
	v_mov_b32_e32 v75, v4
	v_mov_b32_e32 v76, v4
	v_mov_b32_e32 v77, v4
	v_mov_b32_e32 v78, v4
	v_mov_b32_e32 v79, v4
	v_mov_b32_e32 v80, v4
	v_mov_b32_e32 v81, v4
	v_mov_b32_e32 v82, v4
	v_mov_b32_e32 v83, v4
	v_mov_b32_e32 v92, v4
	v_mov_b32_e32 v93, v4
	v_mov_b32_e32 v94, v4
	v_mov_b32_e32 v95, v4
	v_mov_b32_e32 v96, v4
	v_mov_b32_e32 v97, v4
	v_mov_b32_e32 v98, v4
	v_mov_b32_e32 v99, v4
	v_mov_b32_e32 v108, v4
	v_mov_b32_e32 v109, v4
	v_mov_b32_e32 v110, v4
	v_mov_b32_e32 v111, v4
	v_mov_b32_e32 v112, v4
	v_mov_b32_e32 v113, v4
	v_mov_b32_e32 v114, v4
	v_mov_b32_e32 v115, v4
	v_mov_b32_e32 v84, v4
	v_mov_b32_e32 v85, v4
	v_mov_b32_e32 v86, v4
	v_mov_b32_e32 v87, v4
	v_mov_b32_e32 v88, v4
	v_mov_b32_e32 v89, v4
	v_mov_b32_e32 v90, v4
	v_mov_b32_e32 v91, v4
	v_mov_b32_e32 v100, v4
	v_mov_b32_e32 v101, v4
	v_mov_b32_e32 v102, v4
	v_mov_b32_e32 v103, v4
	v_mov_b32_e32 v104, v4
	v_mov_b32_e32 v105, v4
	v_mov_b32_e32 v106, v4
	v_mov_b32_e32 v107, v4
	v_mov_b32_e32 v116, v4
	v_mov_b32_e32 v117, v4
	v_mov_b32_e32 v118, v4
	v_mov_b32_e32 v119, v4
	v_mov_b32_e32 v120, v4
	v_mov_b32_e32 v121, v4
	v_mov_b32_e32 v122, v4
	v_mov_b32_e32 v123, v4
	v_mov_b32_e32 v124, v4
	v_mov_b32_e32 v125, v4
	v_mov_b32_e32 v126, v4
	v_mov_b32_e32 v127, v4
	v_mov_b32_e32 v128, v4
	v_mov_b32_e32 v129, v4
	v_mov_b32_e32 v130, v4
	v_mov_b32_e32 v131, v4
	.p2align	6

.LBB0_341:
	s_ashr_i32 s29, s28, 31
	s_lshl_b64 s[30:31], s[28:29], 18
	s_add_u32 s30, s6, s30
	s_addc_u32 s31, s7, s31
	s_and_b64 s[34:35], s[42:43], exec
	s_cselect_b32 s23, s31, s37
	s_cselect_b32 s25, s30, s36
	s_ashr_i32 s27, s26, 31
	s_lshl_b64 s[34:35], s[26:27], 18
	s_add_u32 s34, s8, s34
	s_addc_u32 s35, s9, s35
	s_and_b64 s[44:45], s[42:43], exec
	s_cselect_b32 s27, s35, s39
	s_cselect_b32 s29, s34, s38
	s_add_u32 s36, s36, 0x20080
	s_addc_u32 s37, s37, 0
	s_add_u32 s53, s38, 0x100
	v_mov_b32_e32 v4, 0
	s_addc_u32 s54, s39, 0
	s_mov_b32 s55, -2
	v_mov_b32_e32 v5, v4
	v_mov_b32_e32 v6, v4
	v_mov_b32_e32 v7, v4
	v_mov_b32_e32 v8, v4
	v_mov_b32_e32 v9, v4
	v_mov_b32_e32 v10, v4
	v_mov_b32_e32 v11, v4
	v_mov_b32_e32 v16, v4
	v_mov_b32_e32 v17, v4
	v_mov_b32_e32 v18, v4
	v_mov_b32_e32 v19, v4
	v_mov_b32_e32 v24, v4
	v_mov_b32_e32 v25, v4
	v_mov_b32_e32 v26, v4
	v_mov_b32_e32 v27, v4
	v_mov_b32_e32 v32, v4
	v_mov_b32_e32 v33, v4
	v_mov_b32_e32 v34, v4
	v_mov_b32_e32 v35, v4
	v_mov_b32_e32 v40, v4
	v_mov_b32_e32 v41, v4
	v_mov_b32_e32 v42, v4
	v_mov_b32_e32 v43, v4
	v_mov_b32_e32 v48, v4
	v_mov_b32_e32 v49, v4
	v_mov_b32_e32 v50, v4
	v_mov_b32_e32 v51, v4
	v_mov_b32_e32 v56, v4
	v_mov_b32_e32 v57, v4
	v_mov_b32_e32 v58, v4
	v_mov_b32_e32 v59, v4
	v_mov_b32_e32 v12, v4
	v_mov_b32_e32 v13, v4
	v_mov_b32_e32 v14, v4
	v_mov_b32_e32 v15, v4
	v_mov_b32_e32 v20, v4
	v_mov_b32_e32 v21, v4
	v_mov_b32_e32 v22, v4
	v_mov_b32_e32 v23, v4
	v_mov_b32_e32 v28, v4
	v_mov_b32_e32 v29, v4
	v_mov_b32_e32 v30, v4
	v_mov_b32_e32 v31, v4
	v_mov_b32_e32 v36, v4
	v_mov_b32_e32 v37, v4
	v_mov_b32_e32 v38, v4
	v_mov_b32_e32 v39, v4
	v_mov_b32_e32 v44, v4
	v_mov_b32_e32 v45, v4
	v_mov_b32_e32 v46, v4
	v_mov_b32_e32 v47, v4
	v_mov_b32_e32 v52, v4
	v_mov_b32_e32 v53, v4
	v_mov_b32_e32 v54, v4
	v_mov_b32_e32 v55, v4
	v_mov_b32_e32 v60, v4
	v_mov_b32_e32 v61, v4
	v_mov_b32_e32 v62, v4
	v_mov_b32_e32 v63, v4
	v_mov_b32_e32 v64, v4
	v_mov_b32_e32 v65, v4
	v_mov_b32_e32 v66, v4
	v_mov_b32_e32 v67, v4
	v_mov_b32_e32 v68, v4
	v_mov_b32_e32 v69, v4
	v_mov_b32_e32 v70, v4
	v_mov_b32_e32 v71, v4
	v_mov_b32_e32 v72, v4
	v_mov_b32_e32 v73, v4
	v_mov_b32_e32 v74, v4
	v_mov_b32_e32 v75, v4
	v_mov_b32_e32 v80, v4
	v_mov_b32_e32 v81, v4
	v_mov_b32_e32 v82, v4
	v_mov_b32_e32 v83, v4
	v_mov_b32_e32 v88, v4
	v_mov_b32_e32 v89, v4
	v_mov_b32_e32 v90, v4
	v_mov_b32_e32 v91, v4
	v_mov_b32_e32 v96, v4
	v_mov_b32_e32 v97, v4
	v_mov_b32_e32 v98, v4
	v_mov_b32_e32 v99, v4
	v_mov_b32_e32 v104, v4
	v_mov_b32_e32 v105, v4
	v_mov_b32_e32 v106, v4
	v_mov_b32_e32 v107, v4
	v_mov_b32_e32 v112, v4
	v_mov_b32_e32 v113, v4
	v_mov_b32_e32 v114, v4
	v_mov_b32_e32 v115, v4
	v_mov_b32_e32 v120, v4
	v_mov_b32_e32 v121, v4
	v_mov_b32_e32 v122, v4
	v_mov_b32_e32 v123, v4
	v_mov_b32_e32 v76, v4
	v_mov_b32_e32 v77, v4
	v_mov_b32_e32 v78, v4
	v_mov_b32_e32 v79, v4
	v_mov_b32_e32 v84, v4
	v_mov_b32_e32 v85, v4
	v_mov_b32_e32 v86, v4
	v_mov_b32_e32 v87, v4
	v_mov_b32_e32 v92, v4
	v_mov_b32_e32 v93, v4
	v_mov_b32_e32 v94, v4
	v_mov_b32_e32 v95, v4
	v_mov_b32_e32 v100, v4
	v_mov_b32_e32 v101, v4
	v_mov_b32_e32 v102, v4
	v_mov_b32_e32 v103, v4
	v_mov_b32_e32 v108, v4
	v_mov_b32_e32 v109, v4
	v_mov_b32_e32 v110, v4
	v_mov_b32_e32 v111, v4
	v_mov_b32_e32 v116, v4
	v_mov_b32_e32 v117, v4
	v_mov_b32_e32 v118, v4
	v_mov_b32_e32 v119, v4
	v_mov_b32_e32 v124, v4
	v_mov_b32_e32 v125, v4
	v_mov_b32_e32 v126, v4
	v_mov_b32_e32 v127, v4
	v_mov_b32_e32 v128, v4
	v_mov_b32_e32 v129, v4
	v_mov_b32_e32 v130, v4
	v_mov_b32_e32 v131, v4
	.p2align	6

.LBB0_654:
	s_ashr_i32 s27, s26, 31
	s_lshl_b64 s[28:29], s[26:27], 18
	s_add_u32 s28, s8, s28
	s_addc_u32 s29, s9, s29
	s_and_b64 s[30:31], s[42:43], exec
	s_cselect_b32 s27, s29, s35
	s_cselect_b32 s50, s28, s34
	s_ashr_i32 s23, s22, 31
	s_lshl_b64 s[30:31], s[22:23], 18
	s_add_u32 s30, s10, s30
	s_addc_u32 s31, s11, s31
	s_and_b64 s[38:39], s[42:43], exec
	s_cselect_b32 s23, s31, s37
	s_cselect_b32 s51, s30, s36
	s_add_u32 s34, s34, 0x20080
	s_addc_u32 s35, s35, 0
	s_add_u32 s52, s36, 0x100
	v_mov_b32_e32 v4, 0
	s_addc_u32 s53, s37, 0
	s_mov_b32 s54, -2
	v_mov_b32_e32 v5, v4
	v_mov_b32_e32 v6, v4
	v_mov_b32_e32 v7, v4
	v_mov_b32_e32 v8, v4
	v_mov_b32_e32 v9, v4
	v_mov_b32_e32 v10, v4
	v_mov_b32_e32 v11, v4
	v_mov_b32_e32 v12, v4
	v_mov_b32_e32 v13, v4
	v_mov_b32_e32 v14, v4
	v_mov_b32_e32 v15, v4
	v_mov_b32_e32 v16, v4
	v_mov_b32_e32 v17, v4
	v_mov_b32_e32 v18, v4
	v_mov_b32_e32 v19, v4
	v_mov_b32_e32 v28, v4
	v_mov_b32_e32 v29, v4
	v_mov_b32_e32 v30, v4
	v_mov_b32_e32 v31, v4
	v_mov_b32_e32 v32, v4
	v_mov_b32_e32 v33, v4
	v_mov_b32_e32 v34, v4
	v_mov_b32_e32 v35, v4
	v_mov_b32_e32 v44, v4
	v_mov_b32_e32 v45, v4
	v_mov_b32_e32 v46, v4
	v_mov_b32_e32 v47, v4
	v_mov_b32_e32 v48, v4
	v_mov_b32_e32 v49, v4
	v_mov_b32_e32 v50, v4
	v_mov_b32_e32 v51, v4
	v_mov_b32_e32 v20, v4
	v_mov_b32_e32 v21, v4
	v_mov_b32_e32 v22, v4
	v_mov_b32_e32 v23, v4
	v_mov_b32_e32 v24, v4
	v_mov_b32_e32 v25, v4
	v_mov_b32_e32 v26, v4
	v_mov_b32_e32 v27, v4
	v_mov_b32_e32 v36, v4
	v_mov_b32_e32 v37, v4
	v_mov_b32_e32 v38, v4
	v_mov_b32_e32 v39, v4
	v_mov_b32_e32 v40, v4
	v_mov_b32_e32 v41, v4
	v_mov_b32_e32 v42, v4
	v_mov_b32_e32 v43, v4
	v_mov_b32_e32 v52, v4
	v_mov_b32_e32 v53, v4
	v_mov_b32_e32 v54, v4
	v_mov_b32_e32 v55, v4
	v_mov_b32_e32 v56, v4
	v_mov_b32_e32 v57, v4
	v_mov_b32_e32 v58, v4
	v_mov_b32_e32 v59, v4
	v_mov_b32_e32 v60, v4
	v_mov_b32_e32 v61, v4
	v_mov_b32_e32 v62, v4
	v_mov_b32_e32 v63, v4
	v_mov_b32_e32 v64, v4
	v_mov_b32_e32 v65, v4
	v_mov_b32_e32 v66, v4
	v_mov_b32_e32 v67, v4
	v_mov_b32_e32 v68, v4
	v_mov_b32_e32 v69, v4
	v_mov_b32_e32 v70, v4
	v_mov_b32_e32 v71, v4
	v_mov_b32_e32 v72, v4
	v_mov_b32_e32 v73, v4
	v_mov_b32_e32 v74, v4
	v_mov_b32_e32 v75, v4
	v_mov_b32_e32 v76, v4
	v_mov_b32_e32 v77, v4
	v_mov_b32_e32 v78, v4
	v_mov_b32_e32 v79, v4
	v_mov_b32_e32 v80, v4
	v_mov_b32_e32 v81, v4
	v_mov_b32_e32 v82, v4
	v_mov_b32_e32 v83, v4
	v_mov_b32_e32 v92, v4
	v_mov_b32_e32 v93, v4
	v_mov_b32_e32 v94, v4
	v_mov_b32_e32 v95, v4
	v_mov_b32_e32 v96, v4
	v_mov_b32_e32 v97, v4
	v_mov_b32_e32 v98, v4
	v_mov_b32_e32 v99, v4
	v_mov_b32_e32 v108, v4
	v_mov_b32_e32 v109, v4
	v_mov_b32_e32 v110, v4
	v_mov_b32_e32 v111, v4
	v_mov_b32_e32 v112, v4
	v_mov_b32_e32 v113, v4
	v_mov_b32_e32 v114, v4
	v_mov_b32_e32 v115, v4
	v_mov_b32_e32 v84, v4
	v_mov_b32_e32 v85, v4
	v_mov_b32_e32 v86, v4
	v_mov_b32_e32 v87, v4
	v_mov_b32_e32 v88, v4
	v_mov_b32_e32 v89, v4
	v_mov_b32_e32 v90, v4
	v_mov_b32_e32 v91, v4
	v_mov_b32_e32 v100, v4
	v_mov_b32_e32 v101, v4
	v_mov_b32_e32 v102, v4
	v_mov_b32_e32 v103, v4
	v_mov_b32_e32 v104, v4
	v_mov_b32_e32 v105, v4
	v_mov_b32_e32 v106, v4
	v_mov_b32_e32 v107, v4
	v_mov_b32_e32 v116, v4
	v_mov_b32_e32 v117, v4
	v_mov_b32_e32 v118, v4
	v_mov_b32_e32 v119, v4
	v_mov_b32_e32 v120, v4
	v_mov_b32_e32 v121, v4
	v_mov_b32_e32 v122, v4
	v_mov_b32_e32 v123, v4
	v_mov_b32_e32 v124, v4
	v_mov_b32_e32 v125, v4
	v_mov_b32_e32 v126, v4
	v_mov_b32_e32 v127, v4
	v_mov_b32_e32 v128, v4
	v_mov_b32_e32 v129, v4
	v_mov_b32_e32 v130, v4
	v_mov_b32_e32 v131, v4
	.p2align	6

.LBB0_672:
	s_ashr_i32 s29, s28, 31
	s_lshl_b64 s[30:31], s[28:29], 18
	s_add_u32 s30, s8, s30
	s_addc_u32 s31, s9, s31
	s_and_b64 s[34:35], s[42:43], exec
	s_cselect_b32 s29, s31, s45
	s_cselect_b32 s37, s30, s44
	s_ashr_i32 s27, s26, 31
	s_lshl_b64 s[34:35], s[26:27], 18
	s_add_u32 s34, s10, s34
	s_addc_u32 s35, s11, s35
	s_and_b64 s[48:49], s[42:43], exec
	s_cselect_b32 s27, s35, s47
	s_cselect_b32 s39, s34, s46
	s_add_u32 s44, s44, 0x20080
	s_addc_u32 s45, s45, 0
	s_add_u32 s56, s46, 0x100
	v_mov_b32_e32 v4, 0
	s_addc_u32 s57, s47, 0
	s_mov_b32 s58, -2
	v_mov_b32_e32 v5, v4
	v_mov_b32_e32 v6, v4
	v_mov_b32_e32 v7, v4
	v_mov_b32_e32 v8, v4
	v_mov_b32_e32 v9, v4
	v_mov_b32_e32 v10, v4
	v_mov_b32_e32 v11, v4
	v_mov_b32_e32 v20, v4
	v_mov_b32_e32 v21, v4
	v_mov_b32_e32 v22, v4
	v_mov_b32_e32 v23, v4
	v_mov_b32_e32 v24, v4
	v_mov_b32_e32 v25, v4
	v_mov_b32_e32 v26, v4
	v_mov_b32_e32 v27, v4
	v_mov_b32_e32 v36, v4
	v_mov_b32_e32 v37, v4
	v_mov_b32_e32 v38, v4
	v_mov_b32_e32 v39, v4
	v_mov_b32_e32 v40, v4
	v_mov_b32_e32 v41, v4
	v_mov_b32_e32 v42, v4
	v_mov_b32_e32 v43, v4
	v_mov_b32_e32 v52, v4
	v_mov_b32_e32 v53, v4
	v_mov_b32_e32 v54, v4
	v_mov_b32_e32 v55, v4
	v_mov_b32_e32 v56, v4
	v_mov_b32_e32 v57, v4
	v_mov_b32_e32 v58, v4
	v_mov_b32_e32 v59, v4
	v_mov_b32_e32 v12, v4
	v_mov_b32_e32 v13, v4
	v_mov_b32_e32 v14, v4
	v_mov_b32_e32 v15, v4
	v_mov_b32_e32 v16, v4
	v_mov_b32_e32 v17, v4
	v_mov_b32_e32 v18, v4
	v_mov_b32_e32 v19, v4
	v_mov_b32_e32 v28, v4
	v_mov_b32_e32 v29, v4
	v_mov_b32_e32 v30, v4
	v_mov_b32_e32 v31, v4
	v_mov_b32_e32 v32, v4
	v_mov_b32_e32 v33, v4
	v_mov_b32_e32 v34, v4
	v_mov_b32_e32 v35, v4
	v_mov_b32_e32 v44, v4
	v_mov_b32_e32 v45, v4
	v_mov_b32_e32 v46, v4
	v_mov_b32_e32 v47, v4
	v_mov_b32_e32 v48, v4
	v_mov_b32_e32 v49, v4
	v_mov_b32_e32 v50, v4
	v_mov_b32_e32 v51, v4
	v_mov_b32_e32 v60, v4
	v_mov_b32_e32 v61, v4
	v_mov_b32_e32 v62, v4
	v_mov_b32_e32 v63, v4
	v_mov_b32_e32 v64, v4
	v_mov_b32_e32 v65, v4
	v_mov_b32_e32 v66, v4
	v_mov_b32_e32 v67, v4
	v_mov_b32_e32 v68, v4
	v_mov_b32_e32 v69, v4
	v_mov_b32_e32 v70, v4
	v_mov_b32_e32 v71, v4
	v_mov_b32_e32 v72, v4
	v_mov_b32_e32 v73, v4
	v_mov_b32_e32 v74, v4
	v_mov_b32_e32 v75, v4
	v_mov_b32_e32 v84, v4
	v_mov_b32_e32 v85, v4
	v_mov_b32_e32 v86, v4
	v_mov_b32_e32 v87, v4
	v_mov_b32_e32 v88, v4
	v_mov_b32_e32 v89, v4
	v_mov_b32_e32 v90, v4
	v_mov_b32_e32 v91, v4
	v_mov_b32_e32 v100, v4
	v_mov_b32_e32 v101, v4
	v_mov_b32_e32 v102, v4
	v_mov_b32_e32 v103, v4
	v_mov_b32_e32 v104, v4
	v_mov_b32_e32 v105, v4
	v_mov_b32_e32 v106, v4
	v_mov_b32_e32 v107, v4
	v_mov_b32_e32 v116, v4
	v_mov_b32_e32 v117, v4
	v_mov_b32_e32 v118, v4
	v_mov_b32_e32 v119, v4
	v_mov_b32_e32 v120, v4
	v_mov_b32_e32 v121, v4
	v_mov_b32_e32 v122, v4
	v_mov_b32_e32 v123, v4
	v_mov_b32_e32 v76, v4
	v_mov_b32_e32 v77, v4
	v_mov_b32_e32 v78, v4
	v_mov_b32_e32 v79, v4
	v_mov_b32_e32 v80, v4
	v_mov_b32_e32 v81, v4
	v_mov_b32_e32 v82, v4
	v_mov_b32_e32 v83, v4
	v_mov_b32_e32 v92, v4
	v_mov_b32_e32 v93, v4
	v_mov_b32_e32 v94, v4
	v_mov_b32_e32 v95, v4
	v_mov_b32_e32 v96, v4
	v_mov_b32_e32 v97, v4
	v_mov_b32_e32 v98, v4
	v_mov_b32_e32 v99, v4
	v_mov_b32_e32 v108, v4
	v_mov_b32_e32 v109, v4
	v_mov_b32_e32 v110, v4
	v_mov_b32_e32 v111, v4
	v_mov_b32_e32 v112, v4
	v_mov_b32_e32 v113, v4
	v_mov_b32_e32 v114, v4
	v_mov_b32_e32 v115, v4
	v_mov_b32_e32 v124, v4
	v_mov_b32_e32 v125, v4
	v_mov_b32_e32 v126, v4
	v_mov_b32_e32 v127, v4
	v_mov_b32_e32 v128, v4
	v_mov_b32_e32 v129, v4
	v_mov_b32_e32 v130, v4
	v_mov_b32_e32 v131, v4
	.p2align	6

.LBB0_704:
	s_ashr_i32 s21, s20, 31
	s_lshl_b64 s[22:23], s[20:21], 19
	s_add_u32 s22, s5, s22
	s_addc_u32 s23, s6, s23
	s_and_b64 s[24:25], s[42:43], exec
	s_cselect_b32 s21, s23, s29
	s_cselect_b32 s47, s22, s28
	s_ashr_i32 s19, s18, 31
	s_lshl_b64 s[24:25], s[18:19], 19
	s_add_u32 s24, s7, s24
	s_addc_u32 s25, s8, s25
	s_and_b64 s[34:35], s[42:43], exec
	s_cselect_b32 s19, s25, s31
	s_cselect_b32 s48, s24, s30
	s_add_u32 s28, s28, 0x40080
	s_addc_u32 s29, s29, 0
	s_add_u32 s49, s30, 0x100
	v_mov_b32_e32 v4, 0
	s_addc_u32 s50, s31, 0
	s_mov_b32 s51, -2
	v_mov_b32_e32 v5, v4
	v_mov_b32_e32 v6, v4
	v_mov_b32_e32 v7, v4
	v_mov_b32_e32 v8, v4
	v_mov_b32_e32 v9, v4
	v_mov_b32_e32 v10, v4
	v_mov_b32_e32 v11, v4
	v_mov_b32_e32 v16, v4
	v_mov_b32_e32 v17, v4
	v_mov_b32_e32 v18, v4
	v_mov_b32_e32 v19, v4
	v_mov_b32_e32 v24, v4
	v_mov_b32_e32 v25, v4
	v_mov_b32_e32 v26, v4
	v_mov_b32_e32 v27, v4
	v_mov_b32_e32 v32, v4
	v_mov_b32_e32 v33, v4
	v_mov_b32_e32 v34, v4
	v_mov_b32_e32 v35, v4
	v_mov_b32_e32 v40, v4
	v_mov_b32_e32 v41, v4
	v_mov_b32_e32 v42, v4
	v_mov_b32_e32 v43, v4
	v_mov_b32_e32 v48, v4
	v_mov_b32_e32 v49, v4
	v_mov_b32_e32 v50, v4
	v_mov_b32_e32 v51, v4
	v_mov_b32_e32 v56, v4
	v_mov_b32_e32 v57, v4
	v_mov_b32_e32 v58, v4
	v_mov_b32_e32 v59, v4
	v_mov_b32_e32 v12, v4
	v_mov_b32_e32 v13, v4
	v_mov_b32_e32 v14, v4
	v_mov_b32_e32 v15, v4
	v_mov_b32_e32 v20, v4
	v_mov_b32_e32 v21, v4
	v_mov_b32_e32 v22, v4
	v_mov_b32_e32 v23, v4
	v_mov_b32_e32 v28, v4
	v_mov_b32_e32 v29, v4
	v_mov_b32_e32 v30, v4
	v_mov_b32_e32 v31, v4
	v_mov_b32_e32 v36, v4
	v_mov_b32_e32 v37, v4
	v_mov_b32_e32 v38, v4
	v_mov_b32_e32 v39, v4
	v_mov_b32_e32 v44, v4
	v_mov_b32_e32 v45, v4
	v_mov_b32_e32 v46, v4
	v_mov_b32_e32 v47, v4
	v_mov_b32_e32 v52, v4
	v_mov_b32_e32 v53, v4
	v_mov_b32_e32 v54, v4
	v_mov_b32_e32 v55, v4
	v_mov_b32_e32 v60, v4
	v_mov_b32_e32 v61, v4
	v_mov_b32_e32 v62, v4
	v_mov_b32_e32 v63, v4
	v_mov_b32_e32 v64, v4
	v_mov_b32_e32 v65, v4
	v_mov_b32_e32 v66, v4
	v_mov_b32_e32 v67, v4
	v_mov_b32_e32 v68, v4
	v_mov_b32_e32 v69, v4
	v_mov_b32_e32 v70, v4
	v_mov_b32_e32 v71, v4
	v_mov_b32_e32 v72, v4
	v_mov_b32_e32 v73, v4
	v_mov_b32_e32 v74, v4
	v_mov_b32_e32 v75, v4
	v_mov_b32_e32 v80, v4
	v_mov_b32_e32 v81, v4
	v_mov_b32_e32 v82, v4
	v_mov_b32_e32 v83, v4
	v_mov_b32_e32 v88, v4
	v_mov_b32_e32 v89, v4
	v_mov_b32_e32 v90, v4
	v_mov_b32_e32 v91, v4
	v_mov_b32_e32 v96, v4
	v_mov_b32_e32 v97, v4
	v_mov_b32_e32 v98, v4
	v_mov_b32_e32 v99, v4
	v_mov_b32_e32 v104, v4
	v_mov_b32_e32 v105, v4
	v_mov_b32_e32 v106, v4
	v_mov_b32_e32 v107, v4
	v_mov_b32_e32 v116, v4
	v_mov_b32_e32 v117, v4
	v_mov_b32_e32 v118, v4
	v_mov_b32_e32 v119, v4
	v_mov_b32_e32 v120, v4
	v_mov_b32_e32 v121, v4
	v_mov_b32_e32 v122, v4
	v_mov_b32_e32 v123, v4
	v_mov_b32_e32 v76, v4
	v_mov_b32_e32 v77, v4
	v_mov_b32_e32 v78, v4
	v_mov_b32_e32 v79, v4
	v_mov_b32_e32 v84, v4
	v_mov_b32_e32 v85, v4
	v_mov_b32_e32 v86, v4
	v_mov_b32_e32 v87, v4
	v_mov_b32_e32 v92, v4
	v_mov_b32_e32 v93, v4
	v_mov_b32_e32 v94, v4
	v_mov_b32_e32 v95, v4
	v_mov_b32_e32 v100, v4
	v_mov_b32_e32 v101, v4
	v_mov_b32_e32 v102, v4
	v_mov_b32_e32 v103, v4
	v_mov_b32_e32 v108, v4
	v_mov_b32_e32 v109, v4
	v_mov_b32_e32 v110, v4
	v_mov_b32_e32 v111, v4
	v_mov_b32_e32 v112, v4
	v_mov_b32_e32 v113, v4
	v_mov_b32_e32 v114, v4
	v_mov_b32_e32 v115, v4
	v_mov_b32_e32 v140, v4
	v_mov_b32_e32 v141, v4
	v_mov_b32_e32 v142, v4
	v_mov_b32_e32 v143, v4
	v_mov_b32_e32 v144, v4
	v_mov_b32_e32 v145, v4
	v_mov_b32_e32 v146, v4
	v_mov_b32_e32 v147, v4
	.p2align	6

.LBB0_1241:
	s_ashr_i32 s23, s22, 31
	s_lshl_b64 s[24:25], s[22:23], 20
	s_add_u32 s21, s8, s24
	s_addc_u32 s23, s9, s25
	s_and_b64 s[24:25], s[26:27], exec
	s_cselect_b32 s25, s23, s35
	s_cselect_b32 s24, s21, s34
	s_ashr_i32 s21, s20, 31
	s_lshl_b64 s[38:39], s[20:21], 20
	s_add_u32 s21, s10, s38
	s_addc_u32 s23, s11, s39
	s_and_b64 s[26:27], s[26:27], exec
	s_cselect_b32 s27, s23, s37
	s_cselect_b32 s26, s21, s36
	s_add_u32 s34, s34, 0x80080
	s_addc_u32 s35, s35, 0
	s_add_u32 s21, s36, 0x100
	v_mov_b32_e32 v4, 0
	s_addc_u32 s23, s37, 0
	s_mov_b32 s29, -2
	v_mov_b32_e32 v5, v4
	v_mov_b32_e32 v6, v4
	v_mov_b32_e32 v7, v4
	v_mov_b32_e32 v8, v4
	v_mov_b32_e32 v9, v4
	v_mov_b32_e32 v10, v4
	v_mov_b32_e32 v11, v4
	v_mov_b32_e32 v16, v4
	v_mov_b32_e32 v17, v4
	v_mov_b32_e32 v18, v4
	v_mov_b32_e32 v19, v4
	v_mov_b32_e32 v24, v4
	v_mov_b32_e32 v25, v4
	v_mov_b32_e32 v26, v4
	v_mov_b32_e32 v27, v4
	v_mov_b32_e32 v32, v4
	v_mov_b32_e32 v33, v4
	v_mov_b32_e32 v34, v4
	v_mov_b32_e32 v35, v4
	v_mov_b32_e32 v40, v4
	v_mov_b32_e32 v41, v4
	v_mov_b32_e32 v42, v4
	v_mov_b32_e32 v43, v4
	v_mov_b32_e32 v48, v4
	v_mov_b32_e32 v49, v4
	v_mov_b32_e32 v50, v4
	v_mov_b32_e32 v51, v4
	v_mov_b32_e32 v56, v4
	v_mov_b32_e32 v57, v4
	v_mov_b32_e32 v58, v4
	v_mov_b32_e32 v59, v4
	v_mov_b32_e32 v12, v4
	v_mov_b32_e32 v13, v4
	v_mov_b32_e32 v14, v4
	v_mov_b32_e32 v15, v4
	v_mov_b32_e32 v20, v4
	v_mov_b32_e32 v21, v4
	v_mov_b32_e32 v22, v4
	v_mov_b32_e32 v23, v4
	v_mov_b32_e32 v28, v4
	v_mov_b32_e32 v29, v4
	v_mov_b32_e32 v30, v4
	v_mov_b32_e32 v31, v4
	v_mov_b32_e32 v36, v4
	v_mov_b32_e32 v37, v4
	v_mov_b32_e32 v38, v4
	v_mov_b32_e32 v39, v4
	v_mov_b32_e32 v44, v4
	v_mov_b32_e32 v45, v4
	v_mov_b32_e32 v46, v4
	v_mov_b32_e32 v47, v4
	v_mov_b32_e32 v52, v4
	v_mov_b32_e32 v53, v4
	v_mov_b32_e32 v54, v4
	v_mov_b32_e32 v55, v4
	v_mov_b32_e32 v60, v4
	v_mov_b32_e32 v61, v4
	v_mov_b32_e32 v62, v4
	v_mov_b32_e32 v63, v4
	v_mov_b32_e32 v64, v4
	v_mov_b32_e32 v65, v4
	v_mov_b32_e32 v66, v4
	v_mov_b32_e32 v67, v4
	v_mov_b32_e32 v68, v4
	v_mov_b32_e32 v69, v4
	v_mov_b32_e32 v70, v4
	v_mov_b32_e32 v71, v4
	v_mov_b32_e32 v72, v4
	v_mov_b32_e32 v73, v4
	v_mov_b32_e32 v74, v4
	v_mov_b32_e32 v75, v4
	v_mov_b32_e32 v80, v4
	v_mov_b32_e32 v81, v4
	v_mov_b32_e32 v82, v4
	v_mov_b32_e32 v83, v4
	v_mov_b32_e32 v88, v4
	v_mov_b32_e32 v89, v4
	v_mov_b32_e32 v90, v4
	v_mov_b32_e32 v91, v4
	v_mov_b32_e32 v96, v4
	v_mov_b32_e32 v97, v4
	v_mov_b32_e32 v98, v4
	v_mov_b32_e32 v99, v4
	v_mov_b32_e32 v104, v4
	v_mov_b32_e32 v105, v4
	v_mov_b32_e32 v106, v4
	v_mov_b32_e32 v107, v4
	v_mov_b32_e32 v116, v4
	v_mov_b32_e32 v117, v4
	v_mov_b32_e32 v118, v4
	v_mov_b32_e32 v119, v4
	v_mov_b32_e32 v120, v4
	v_mov_b32_e32 v121, v4
	v_mov_b32_e32 v122, v4
	v_mov_b32_e32 v123, v4
	v_mov_b32_e32 v76, v4
	v_mov_b32_e32 v77, v4
	v_mov_b32_e32 v78, v4
	v_mov_b32_e32 v79, v4
	v_mov_b32_e32 v84, v4
	v_mov_b32_e32 v85, v4
	v_mov_b32_e32 v86, v4
	v_mov_b32_e32 v87, v4
	v_mov_b32_e32 v92, v4
	v_mov_b32_e32 v93, v4
	v_mov_b32_e32 v94, v4
	v_mov_b32_e32 v95, v4
	v_mov_b32_e32 v100, v4
	v_mov_b32_e32 v101, v4
	v_mov_b32_e32 v102, v4
	v_mov_b32_e32 v103, v4
	v_mov_b32_e32 v108, v4
	v_mov_b32_e32 v109, v4
	v_mov_b32_e32 v110, v4
	v_mov_b32_e32 v111, v4
	v_mov_b32_e32 v112, v4
	v_mov_b32_e32 v113, v4
	v_mov_b32_e32 v114, v4
	v_mov_b32_e32 v115, v4
	v_mov_b32_e32 v124, v4
	v_mov_b32_e32 v125, v4
	v_mov_b32_e32 v126, v4
	v_mov_b32_e32 v127, v4
	v_mov_b32_e32 v128, v4
	v_mov_b32_e32 v129, v4
	v_mov_b32_e32 v130, v4
	v_mov_b32_e32 v131, v4
	.p2align	6

.LBB0_1259:
	s_ashr_i32 s21, s20, 31
	s_lshl_b64 s[22:23], s[20:21], 19
	s_add_u32 s19, s8, s22
	s_addc_u32 s21, s9, s23
	s_and_b64 s[22:23], s[24:25], exec
	s_cselect_b32 s23, s21, s31
	s_cselect_b32 s22, s19, s30
	s_ashr_i32 s19, s18, 31
	s_lshl_b64 s[36:37], s[18:19], 19
	s_add_u32 s19, s10, s36
	s_addc_u32 s21, s11, s37
	s_and_b64 s[24:25], s[24:25], exec
	s_cselect_b32 s25, s21, s35
	s_cselect_b32 s24, s19, s34
	s_add_u32 s30, s30, 0x40080
	s_addc_u32 s31, s31, 0
	s_add_u32 s19, s34, 0x100
	v_mov_b32_e32 v4, 0
	s_addc_u32 s21, s35, 0
	s_mov_b32 s27, -2
	v_mov_b32_e32 v5, v4
	v_mov_b32_e32 v6, v4
	v_mov_b32_e32 v7, v4
	v_mov_b32_e32 v8, v4
	v_mov_b32_e32 v9, v4
	v_mov_b32_e32 v10, v4
	v_mov_b32_e32 v11, v4
	v_mov_b32_e32 v16, v4
	v_mov_b32_e32 v17, v4
	v_mov_b32_e32 v18, v4
	v_mov_b32_e32 v19, v4
	v_mov_b32_e32 v24, v4
	v_mov_b32_e32 v25, v4
	v_mov_b32_e32 v26, v4
	v_mov_b32_e32 v27, v4
	v_mov_b32_e32 v32, v4
	v_mov_b32_e32 v33, v4
	v_mov_b32_e32 v34, v4
	v_mov_b32_e32 v35, v4
	v_mov_b32_e32 v40, v4
	v_mov_b32_e32 v41, v4
	v_mov_b32_e32 v42, v4
	v_mov_b32_e32 v43, v4
	v_mov_b32_e32 v48, v4
	v_mov_b32_e32 v49, v4
	v_mov_b32_e32 v50, v4
	v_mov_b32_e32 v51, v4
	v_mov_b32_e32 v56, v4
	v_mov_b32_e32 v57, v4
	v_mov_b32_e32 v58, v4
	v_mov_b32_e32 v59, v4
	v_mov_b32_e32 v12, v4
	v_mov_b32_e32 v13, v4
	v_mov_b32_e32 v14, v4
	v_mov_b32_e32 v15, v4
	v_mov_b32_e32 v20, v4
	v_mov_b32_e32 v21, v4
	v_mov_b32_e32 v22, v4
	v_mov_b32_e32 v23, v4
	v_mov_b32_e32 v28, v4
	v_mov_b32_e32 v29, v4
	v_mov_b32_e32 v30, v4
	v_mov_b32_e32 v31, v4
	v_mov_b32_e32 v36, v4
	v_mov_b32_e32 v37, v4
	v_mov_b32_e32 v38, v4
	v_mov_b32_e32 v39, v4
	v_mov_b32_e32 v44, v4
	v_mov_b32_e32 v45, v4
	v_mov_b32_e32 v46, v4
	v_mov_b32_e32 v47, v4
	v_mov_b32_e32 v52, v4
	v_mov_b32_e32 v53, v4
	v_mov_b32_e32 v54, v4
	v_mov_b32_e32 v55, v4
	v_mov_b32_e32 v60, v4
	v_mov_b32_e32 v61, v4
	v_mov_b32_e32 v62, v4
	v_mov_b32_e32 v63, v4
	v_mov_b32_e32 v64, v4
	v_mov_b32_e32 v65, v4
	v_mov_b32_e32 v66, v4
	v_mov_b32_e32 v67, v4
	v_mov_b32_e32 v68, v4
	v_mov_b32_e32 v69, v4
	v_mov_b32_e32 v70, v4
	v_mov_b32_e32 v71, v4
	v_mov_b32_e32 v72, v4
	v_mov_b32_e32 v73, v4
	v_mov_b32_e32 v74, v4
	v_mov_b32_e32 v75, v4
	v_mov_b32_e32 v80, v4
	v_mov_b32_e32 v81, v4
	v_mov_b32_e32 v82, v4
	v_mov_b32_e32 v83, v4
	v_mov_b32_e32 v88, v4
	v_mov_b32_e32 v89, v4
	v_mov_b32_e32 v90, v4
	v_mov_b32_e32 v91, v4
	v_mov_b32_e32 v96, v4
	v_mov_b32_e32 v97, v4
	v_mov_b32_e32 v98, v4
	v_mov_b32_e32 v99, v4
	v_mov_b32_e32 v104, v4
	v_mov_b32_e32 v105, v4
	v_mov_b32_e32 v106, v4
	v_mov_b32_e32 v107, v4
	v_mov_b32_e32 v116, v4
	v_mov_b32_e32 v117, v4
	v_mov_b32_e32 v118, v4
	v_mov_b32_e32 v119, v4
	v_mov_b32_e32 v120, v4
	v_mov_b32_e32 v121, v4
	v_mov_b32_e32 v122, v4
	v_mov_b32_e32 v123, v4
	v_mov_b32_e32 v76, v4
	v_mov_b32_e32 v77, v4
	v_mov_b32_e32 v78, v4
	v_mov_b32_e32 v79, v4
	v_mov_b32_e32 v84, v4
	v_mov_b32_e32 v85, v4
	v_mov_b32_e32 v86, v4
	v_mov_b32_e32 v87, v4
	v_mov_b32_e32 v92, v4
	v_mov_b32_e32 v93, v4
	v_mov_b32_e32 v94, v4
	v_mov_b32_e32 v95, v4
	v_mov_b32_e32 v100, v4
	v_mov_b32_e32 v101, v4
	v_mov_b32_e32 v102, v4
	v_mov_b32_e32 v103, v4
	v_mov_b32_e32 v108, v4
	v_mov_b32_e32 v109, v4
	v_mov_b32_e32 v110, v4
	v_mov_b32_e32 v111, v4
	v_mov_b32_e32 v112, v4
	v_mov_b32_e32 v113, v4
	v_mov_b32_e32 v114, v4
	v_mov_b32_e32 v115, v4
	v_mov_b32_e32 v124, v4
	v_mov_b32_e32 v125, v4
	v_mov_b32_e32 v126, v4
	v_mov_b32_e32 v127, v4
	v_mov_b32_e32 v128, v4
	v_mov_b32_e32 v129, v4
	v_mov_b32_e32 v130, v4
	v_mov_b32_e32 v131, v4
	.p2align	6

.LBB0_1277:
	s_ashr_i32 s19, s18, 31
	s_lshl_b64 s[20:21], s[18:19], 19
	s_add_u32 s1, s9, s20
	s_addc_u32 s19, s10, s21
	s_and_b64 s[20:21], s[22:23], exec
	s_cselect_b32 s21, s19, s29
	s_cselect_b32 s20, s1, s28
	s_ashr_i32 s1, s0, 31
	s_lshl_b64 s[34:35], s[0:1], 19
	s_add_u32 s1, s7, s34
	s_addc_u32 s19, s8, s35
	s_and_b64 s[22:23], s[22:23], exec
	s_cselect_b32 s23, s19, s31
	s_cselect_b32 s22, s1, s30
	s_add_u32 s28, s28, 0x40080
	s_addc_u32 s29, s29, 0
	s_add_u32 s1, s30, 0x100
	v_mov_b32_e32 v4, 0
	s_addc_u32 s19, s31, 0
	s_mov_b32 s25, -2
	v_mov_b32_e32 v5, v4
	v_mov_b32_e32 v6, v4
	v_mov_b32_e32 v7, v4
	v_mov_b32_e32 v8, v4
	v_mov_b32_e32 v9, v4
	v_mov_b32_e32 v10, v4
	v_mov_b32_e32 v11, v4
	v_mov_b32_e32 v16, v4
	v_mov_b32_e32 v17, v4
	v_mov_b32_e32 v18, v4
	v_mov_b32_e32 v19, v4
	v_mov_b32_e32 v24, v4
	v_mov_b32_e32 v25, v4
	v_mov_b32_e32 v26, v4
	v_mov_b32_e32 v27, v4
	v_mov_b32_e32 v32, v4
	v_mov_b32_e32 v33, v4
	v_mov_b32_e32 v34, v4
	v_mov_b32_e32 v35, v4
	v_mov_b32_e32 v40, v4
	v_mov_b32_e32 v41, v4
	v_mov_b32_e32 v42, v4
	v_mov_b32_e32 v43, v4
	v_mov_b32_e32 v48, v4
	v_mov_b32_e32 v49, v4
	v_mov_b32_e32 v50, v4
	v_mov_b32_e32 v51, v4
	v_mov_b32_e32 v56, v4
	v_mov_b32_e32 v57, v4
	v_mov_b32_e32 v58, v4
	v_mov_b32_e32 v59, v4
	v_mov_b32_e32 v12, v4
	v_mov_b32_e32 v13, v4
	v_mov_b32_e32 v14, v4
	v_mov_b32_e32 v15, v4
	v_mov_b32_e32 v20, v4
	v_mov_b32_e32 v21, v4
	v_mov_b32_e32 v22, v4
	v_mov_b32_e32 v23, v4
	v_mov_b32_e32 v28, v4
	v_mov_b32_e32 v29, v4
	v_mov_b32_e32 v30, v4
	v_mov_b32_e32 v31, v4
	v_mov_b32_e32 v36, v4
	v_mov_b32_e32 v37, v4
	v_mov_b32_e32 v38, v4
	v_mov_b32_e32 v39, v4
	v_mov_b32_e32 v44, v4
	v_mov_b32_e32 v45, v4
	v_mov_b32_e32 v46, v4
	v_mov_b32_e32 v47, v4
	v_mov_b32_e32 v52, v4
	v_mov_b32_e32 v53, v4
	v_mov_b32_e32 v54, v4
	v_mov_b32_e32 v55, v4
	v_mov_b32_e32 v60, v4
	v_mov_b32_e32 v61, v4
	v_mov_b32_e32 v62, v4
	v_mov_b32_e32 v63, v4
	v_mov_b32_e32 v64, v4
	v_mov_b32_e32 v65, v4
	v_mov_b32_e32 v66, v4
	v_mov_b32_e32 v67, v4
	v_mov_b32_e32 v68, v4
	v_mov_b32_e32 v69, v4
	v_mov_b32_e32 v70, v4
	v_mov_b32_e32 v71, v4
	v_mov_b32_e32 v72, v4
	v_mov_b32_e32 v73, v4
	v_mov_b32_e32 v74, v4
	v_mov_b32_e32 v75, v4
	v_mov_b32_e32 v80, v4
	v_mov_b32_e32 v81, v4
	v_mov_b32_e32 v82, v4
	v_mov_b32_e32 v83, v4
	v_mov_b32_e32 v88, v4
	v_mov_b32_e32 v89, v4
	v_mov_b32_e32 v90, v4
	v_mov_b32_e32 v91, v4
	v_mov_b32_e32 v96, v4
	v_mov_b32_e32 v97, v4
	v_mov_b32_e32 v98, v4
	v_mov_b32_e32 v99, v4
	v_mov_b32_e32 v104, v4
	v_mov_b32_e32 v105, v4
	v_mov_b32_e32 v106, v4
	v_mov_b32_e32 v107, v4
	v_mov_b32_e32 v116, v4
	v_mov_b32_e32 v117, v4
	v_mov_b32_e32 v118, v4
	v_mov_b32_e32 v119, v4
	v_mov_b32_e32 v120, v4
	v_mov_b32_e32 v121, v4
	v_mov_b32_e32 v122, v4
	v_mov_b32_e32 v123, v4
	v_mov_b32_e32 v76, v4
	v_mov_b32_e32 v77, v4
	v_mov_b32_e32 v78, v4
	v_mov_b32_e32 v79, v4
	v_mov_b32_e32 v84, v4
	v_mov_b32_e32 v85, v4
	v_mov_b32_e32 v86, v4
	v_mov_b32_e32 v87, v4
	v_mov_b32_e32 v92, v4
	v_mov_b32_e32 v93, v4
	v_mov_b32_e32 v94, v4
	v_mov_b32_e32 v95, v4
	v_mov_b32_e32 v100, v4
	v_mov_b32_e32 v101, v4
	v_mov_b32_e32 v102, v4
	v_mov_b32_e32 v103, v4
	v_mov_b32_e32 v108, v4
	v_mov_b32_e32 v109, v4
	v_mov_b32_e32 v110, v4
	v_mov_b32_e32 v111, v4
	v_mov_b32_e32 v112, v4
	v_mov_b32_e32 v113, v4
	v_mov_b32_e32 v114, v4
	v_mov_b32_e32 v115, v4
	v_mov_b32_e32 v124, v4
	v_mov_b32_e32 v125, v4
	v_mov_b32_e32 v126, v4
	v_mov_b32_e32 v127, v4
	v_mov_b32_e32 v128, v4
	v_mov_b32_e32 v129, v4
	v_mov_b32_e32 v130, v4
	v_mov_b32_e32 v131, v4
	.p2align	6

.LBB0_1402:
	s_ashr_i32 s21, s20, 31
	s_lshl_b64 s[22:23], s[20:21], 20
	s_add_u32 s22, s7, s22
	s_addc_u32 s23, s10, s23
	s_and_b64 s[24:25], s[42:43], exec
	s_cselect_b32 s21, s23, s29
	s_cselect_b32 s53, s22, s28
	s_ashr_i32 s19, s18, 31
	s_lshl_b64 s[24:25], s[18:19], 20
	s_add_u32 s24, s11, s24
	s_addc_u32 s25, s33, s25
	s_and_b64 s[34:35], s[42:43], exec
	s_cselect_b32 s19, s25, s31
	s_cselect_b32 s54, s24, s30
	s_add_u32 s28, s28, 0x80080
	s_addc_u32 s29, s29, 0
	s_add_u32 s55, s30, 0x100
	v_mov_b32_e32 v4, 0
	s_addc_u32 s56, s31, 0
	s_mov_b32 s57, -2
	v_mov_b32_e32 v5, v4
	v_mov_b32_e32 v6, v4
	v_mov_b32_e32 v7, v4
	v_mov_b32_e32 v8, v4
	v_mov_b32_e32 v9, v4
	v_mov_b32_e32 v10, v4
	v_mov_b32_e32 v11, v4
	v_mov_b32_e32 v20, v4
	v_mov_b32_e32 v21, v4
	v_mov_b32_e32 v22, v4
	v_mov_b32_e32 v23, v4
	v_mov_b32_e32 v24, v4
	v_mov_b32_e32 v25, v4
	v_mov_b32_e32 v26, v4
	v_mov_b32_e32 v27, v4
	v_mov_b32_e32 v36, v4
	v_mov_b32_e32 v37, v4
	v_mov_b32_e32 v38, v4
	v_mov_b32_e32 v39, v4
	v_mov_b32_e32 v40, v4
	v_mov_b32_e32 v41, v4
	v_mov_b32_e32 v42, v4
	v_mov_b32_e32 v43, v4
	v_mov_b32_e32 v44, v4
	v_mov_b32_e32 v45, v4
	v_mov_b32_e32 v46, v4
	v_mov_b32_e32 v47, v4
	v_mov_b32_e32 v48, v4
	v_mov_b32_e32 v49, v4
	v_mov_b32_e32 v50, v4
	v_mov_b32_e32 v51, v4
	v_mov_b32_e32 v12, v4
	v_mov_b32_e32 v13, v4
	v_mov_b32_e32 v14, v4
	v_mov_b32_e32 v15, v4
	v_mov_b32_e32 v16, v4
	v_mov_b32_e32 v17, v4
	v_mov_b32_e32 v18, v4
	v_mov_b32_e32 v19, v4
	v_mov_b32_e32 v28, v4
	v_mov_b32_e32 v29, v4
	v_mov_b32_e32 v30, v4
	v_mov_b32_e32 v31, v4
	v_mov_b32_e32 v32, v4
	v_mov_b32_e32 v33, v4
	v_mov_b32_e32 v34, v4
	v_mov_b32_e32 v35, v4
	v_mov_b32_e32 v52, v4
	v_mov_b32_e32 v53, v4
	v_mov_b32_e32 v54, v4
	v_mov_b32_e32 v55, v4
	v_mov_b32_e32 v56, v4
	v_mov_b32_e32 v57, v4
	v_mov_b32_e32 v58, v4
	v_mov_b32_e32 v59, v4
	v_mov_b32_e32 v60, v4
	v_mov_b32_e32 v61, v4
	v_mov_b32_e32 v62, v4
	v_mov_b32_e32 v63, v4
	v_mov_b32_e32 v64, v4
	v_mov_b32_e32 v65, v4
	v_mov_b32_e32 v66, v4
	v_mov_b32_e32 v67, v4
	v_mov_b32_e32 v68, v4
	v_mov_b32_e32 v69, v4
	v_mov_b32_e32 v70, v4
	v_mov_b32_e32 v71, v4
	v_mov_b32_e32 v72, v4
	v_mov_b32_e32 v73, v4
	v_mov_b32_e32 v74, v4
	v_mov_b32_e32 v75, v4
	v_mov_b32_e32 v76, v4
	v_mov_b32_e32 v77, v4
	v_mov_b32_e32 v78, v4
	v_mov_b32_e32 v79, v4
	v_mov_b32_e32 v80, v4
	v_mov_b32_e32 v81, v4
	v_mov_b32_e32 v82, v4
	v_mov_b32_e32 v83, v4
	v_mov_b32_e32 v100, v4
	v_mov_b32_e32 v101, v4
	v_mov_b32_e32 v102, v4
	v_mov_b32_e32 v103, v4
	v_mov_b32_e32 v104, v4
	v_mov_b32_e32 v105, v4
	v_mov_b32_e32 v106, v4
	v_mov_b32_e32 v107, v4
	v_mov_b32_e32 v108, v4
	v_mov_b32_e32 v109, v4
	v_mov_b32_e32 v110, v4
	v_mov_b32_e32 v111, v4
	v_mov_b32_e32 v112, v4
	v_mov_b32_e32 v113, v4
	v_mov_b32_e32 v114, v4
	v_mov_b32_e32 v115, v4
	v_mov_b32_e32 v84, v4
	v_mov_b32_e32 v85, v4
	v_mov_b32_e32 v86, v4
	v_mov_b32_e32 v87, v4
	v_mov_b32_e32 v88, v4
	v_mov_b32_e32 v89, v4
	v_mov_b32_e32 v90, v4
	v_mov_b32_e32 v91, v4
	v_mov_b32_e32 v92, v4
	v_mov_b32_e32 v93, v4
	v_mov_b32_e32 v94, v4
	v_mov_b32_e32 v95, v4
	v_mov_b32_e32 v96, v4
	v_mov_b32_e32 v97, v4
	v_mov_b32_e32 v98, v4
	v_mov_b32_e32 v99, v4
	v_mov_b32_e32 v116, v4
	v_mov_b32_e32 v117, v4
	v_mov_b32_e32 v118, v4
	v_mov_b32_e32 v119, v4
	v_mov_b32_e32 v120, v4
	v_mov_b32_e32 v121, v4
	v_mov_b32_e32 v122, v4
	v_mov_b32_e32 v123, v4
	v_mov_b32_e32 v124, v4
	v_mov_b32_e32 v125, v4
	v_mov_b32_e32 v126, v4
	v_mov_b32_e32 v127, v4
	v_mov_b32_e32 v128, v4
	v_mov_b32_e32 v129, v4
	v_mov_b32_e32 v130, v4
	v_mov_b32_e32 v131, v4
	.p2align	6
